# v25: mixers unit deal rebalanced: sample-sgu units move from the slowest wave class (conv+pool+sample-conv+sample-sgu) to the class that had only three units
# speedup vs baseline: 1.0075x; 1.0075x over previous
; __global__ void __launch_bounds__(NWAVES * 64, 2) hybrid_fwd(Args args) {
;     ...
;                     else { if (ui >= 4) break;
;                         const int x = vcu >> 5, cl_ = vcu & 31;
;                         if (wave < 2) { const int a_l = cl_ * 2 + wave; if (ui == 0) u = 64 * x + a_l; else if (ui == 1) u = NU_SGU + 256 * x + 192 + a_l; else break; }
;                         else { const int b_l = cl_ * 6 + (wave - 2);
;                             if (ui == 0) u = NU_SGU + 256 * x + b_l;
;                             else { const int ll = (ui - 1) * 192 + b_l; if (ll >= 512) break;
;                                 if (ll < 128) u = NU_SGU + NU_CONV + 128 * x + ll; else if (ll < 256) u = NU_SGU + NU_CONV + NU_SEG + 128 * x + (ll - 128); else { const int ls = ll - 256; u = NU_SGU + NU_CONV + 2 * NU_SEG + (ls >> 6) * 512 + (16 * x + ((ls >> 2) & 15)) * 4 + (ls & 3); } } } }
.LBB0_86:
	s_cmp_lt_u32 s68, 4
	s_cbranch_scc0 .LBB0_114
	s_and_b64 vcc, exec, s[42:43]
	s_cbranch_vccz .LBB0_99
	s_cmp_eq_u32 s68, 0
	s_mov_b32 s2, 0
	s_cbranch_scc1 .LBB0_100
	s_mul_i32 s2, s68, 0xc0
	s_add_i32 s2, s59, s2
	s_cmp_eq_u32 s68, 3
	s_cbranch_scc0 .Ldeal_ok
	s_cmpk_lt_u32 s2, 0x1c0
	s_cbranch_scc1 .Ldeal_ok
	s_cmpk_lt_u32 s2, 0x200
	s_cbranch_scc1 .LBB0_101
	s_sub_u32 s2, s2, 64
.Ldeal_ok:
	s_cmpk_gt_u32 s2, 0x1ff
	s_cbranch_scc1 .LBB0_101
	s_cmpk_gt_u32 s2, 0x7f
	s_mov_b64 s[4:5], -1
	s_cbranch_scc0 .LBB0_96
	s_cmpk_gt_u32 s2, 0xff
	s_cbranch_scc0 .LBB0_93
	s_lshl_b32 s4, s2, 3
	s_add_i32 s4, s4, 0x7ffff800
	s_and_b32 s4, s4, 0x7ffffe00
	v_readlane_b32 s5, v252, 3
	s_add_i32 s8, s5, s4
	s_mov_b64 s[4:5], 0
